# ctx small-GEMM activation staging: 16 loads issued before the 16 counted waits + ds_writes (was load/vmcnt0/write serial)
# speedup vs baseline: 1.0087x; 1.0087x over previous
; #define LAS __attribute__((address_space(3)))
; template <int MODE>
; __device__ __forceinline__ void ctx_small_gemm(PREF P, unsigned char* shm) {
;     ...
;             for (int ch = tid; ch < ROWS * CPR; ch += 512) { const int row = ch / CPR, c = ch % CPR; const u32x4 v = *(const u32x4*)(Asrc + (size_t)(row_base + row) * K + c * 8);
;                 *(LAS u32x4*)(lds + row * (K * 2) + ((c ^ (row & 15)) << 4)) = v; }
.LBB0_716:
	v_ashrrev_i32_e32 v4, 31, v3
	v_lshrrev_b32_e32 v4, 25, v4
	v_add_u32_e32 v8, v3, v4
	v_ashrrev_i32_e32 v9, 7, v8
	v_add_u32_e32 v4, s20, v9
	v_lshlrev_b32_e32 v6, 10, v9
	v_ashrrev_i32_e32 v5, 31, v4
	v_sub_u32_e32 v6, v2, v6
	v_lshlrev_b64 v[4:5], 11, v[4:5]
	v_ashrrev_i32_e32 v7, 31, v6
	v_lshl_add_u64 v[4:5], s[8:9], 0, v[4:5]
	v_lshl_add_u64 v[4:5], v[6:7], 1, v[4:5]
	global_load_dwordx4 v[64:67], v[4:5], off
	v_and_b32_e32 v8, 0xfffff80, v8
	v_sub_u32_e32 v8, v3, v8
	v_bitop3_b32 v8, v9, v8, 15 bitop3:0x6c
	v_add_u32_e32 v10, 0x200, v3
	v_lshlrev_b32_e32 v14, 11, v9
	v_lshlrev_b32_e32 v8, 4, v8
	v_mov_b32_e32 v3, v10
	v_add_u32_e32 v2, 0x1000, v2
	v_add3_u32 v128, 16, v14, v8
	v_ashrrev_i32_e32 v4, 31, v3
	v_lshrrev_b32_e32 v4, 25, v4
	v_add_u32_e32 v8, v3, v4
	v_ashrrev_i32_e32 v9, 7, v8
	v_add_u32_e32 v4, s20, v9
	v_lshlrev_b32_e32 v6, 10, v9
	v_ashrrev_i32_e32 v5, 31, v4
	v_sub_u32_e32 v6, v2, v6
	v_lshlrev_b64 v[4:5], 11, v[4:5]
	v_ashrrev_i32_e32 v7, 31, v6
	v_lshl_add_u64 v[4:5], s[8:9], 0, v[4:5]
	v_lshl_add_u64 v[4:5], v[6:7], 1, v[4:5]
	global_load_dwordx4 v[68:71], v[4:5], off
	v_and_b32_e32 v8, 0xfffff80, v8
	v_sub_u32_e32 v8, v3, v8
	v_bitop3_b32 v8, v9, v8, 15 bitop3:0x6c
	v_add_u32_e32 v10, 0x200, v3
	v_lshlrev_b32_e32 v14, 11, v9
	v_lshlrev_b32_e32 v8, 4, v8
	v_mov_b32_e32 v3, v10
	v_add_u32_e32 v2, 0x1000, v2
	v_add3_u32 v129, 16, v14, v8
	v_ashrrev_i32_e32 v4, 31, v3
	v_lshrrev_b32_e32 v4, 25, v4
	v_add_u32_e32 v8, v3, v4
	v_ashrrev_i32_e32 v9, 7, v8
	v_add_u32_e32 v4, s20, v9
	v_lshlrev_b32_e32 v6, 10, v9
	v_ashrrev_i32_e32 v5, 31, v4
	v_sub_u32_e32 v6, v2, v6
	v_lshlrev_b64 v[4:5], 11, v[4:5]
	v_ashrrev_i32_e32 v7, 31, v6
	v_lshl_add_u64 v[4:5], s[8:9], 0, v[4:5]
	v_lshl_add_u64 v[4:5], v[6:7], 1, v[4:5]
	global_load_dwordx4 v[72:75], v[4:5], off
	v_and_b32_e32 v8, 0xfffff80, v8
	v_sub_u32_e32 v8, v3, v8
	v_bitop3_b32 v8, v9, v8, 15 bitop3:0x6c
	v_add_u32_e32 v10, 0x200, v3
	v_lshlrev_b32_e32 v14, 11, v9
	v_lshlrev_b32_e32 v8, 4, v8
	v_mov_b32_e32 v3, v10
	v_add_u32_e32 v2, 0x1000, v2
	v_add3_u32 v130, 16, v14, v8
	v_ashrrev_i32_e32 v4, 31, v3
	v_lshrrev_b32_e32 v4, 25, v4
	v_add_u32_e32 v8, v3, v4
	v_ashrrev_i32_e32 v9, 7, v8
	v_add_u32_e32 v4, s20, v9
	v_lshlrev_b32_e32 v6, 10, v9
	v_ashrrev_i32_e32 v5, 31, v4
	v_sub_u32_e32 v6, v2, v6
	v_lshlrev_b64 v[4:5], 11, v[4:5]
	v_ashrrev_i32_e32 v7, 31, v6
	v_lshl_add_u64 v[4:5], s[8:9], 0, v[4:5]
	v_lshl_add_u64 v[4:5], v[6:7], 1, v[4:5]
	global_load_dwordx4 v[76:79], v[4:5], off
	v_and_b32_e32 v8, 0xfffff80, v8
	v_sub_u32_e32 v8, v3, v8
	v_bitop3_b32 v8, v9, v8, 15 bitop3:0x6c
	v_add_u32_e32 v10, 0x200, v3
	v_lshlrev_b32_e32 v14, 11, v9
	v_lshlrev_b32_e32 v8, 4, v8
	v_mov_b32_e32 v3, v10
	v_add_u32_e32 v2, 0x1000, v2
	v_add3_u32 v131, 16, v14, v8
	v_ashrrev_i32_e32 v4, 31, v3
	v_lshrrev_b32_e32 v4, 25, v4
	v_add_u32_e32 v8, v3, v4
	v_ashrrev_i32_e32 v9, 7, v8
	v_add_u32_e32 v4, s20, v9
	v_lshlrev_b32_e32 v6, 10, v9
	v_ashrrev_i32_e32 v5, 31, v4
	v_sub_u32_e32 v6, v2, v6
	v_lshlrev_b64 v[4:5], 11, v[4:5]
	v_ashrrev_i32_e32 v7, 31, v6
	v_lshl_add_u64 v[4:5], s[8:9], 0, v[4:5]
	v_lshl_add_u64 v[4:5], v[6:7], 1, v[4:5]
	global_load_dwordx4 v[80:83], v[4:5], off
	v_and_b32_e32 v8, 0xfffff80, v8
	v_sub_u32_e32 v8, v3, v8
	v_bitop3_b32 v8, v9, v8, 15 bitop3:0x6c
	v_add_u32_e32 v10, 0x200, v3
	v_lshlrev_b32_e32 v14, 11, v9
	v_lshlrev_b32_e32 v8, 4, v8
	v_mov_b32_e32 v3, v10
	v_add_u32_e32 v2, 0x1000, v2
	v_add3_u32 v132, 16, v14, v8
	v_ashrrev_i32_e32 v4, 31, v3
	v_lshrrev_b32_e32 v4, 25, v4
	v_add_u32_e32 v8, v3, v4
	v_ashrrev_i32_e32 v9, 7, v8
	v_add_u32_e32 v4, s20, v9
	v_lshlrev_b32_e32 v6, 10, v9
	v_ashrrev_i32_e32 v5, 31, v4
	v_sub_u32_e32 v6, v2, v6
	v_lshlrev_b64 v[4:5], 11, v[4:5]
	v_ashrrev_i32_e32 v7, 31, v6
	v_lshl_add_u64 v[4:5], s[8:9], 0, v[4:5]
	v_lshl_add_u64 v[4:5], v[6:7], 1, v[4:5]
	global_load_dwordx4 v[84:87], v[4:5], off
	v_and_b32_e32 v8, 0xfffff80, v8
	v_sub_u32_e32 v8, v3, v8
	v_bitop3_b32 v8, v9, v8, 15 bitop3:0x6c
	v_add_u32_e32 v10, 0x200, v3
	v_lshlrev_b32_e32 v14, 11, v9
	v_lshlrev_b32_e32 v8, 4, v8
	v_mov_b32_e32 v3, v10
	v_add_u32_e32 v2, 0x1000, v2
	v_add3_u32 v133, 16, v14, v8
	v_ashrrev_i32_e32 v4, 31, v3
	v_lshrrev_b32_e32 v4, 25, v4
	v_add_u32_e32 v8, v3, v4
	v_ashrrev_i32_e32 v9, 7, v8
	v_add_u32_e32 v4, s20, v9
	v_lshlrev_b32_e32 v6, 10, v9
	v_ashrrev_i32_e32 v5, 31, v4
	v_sub_u32_e32 v6, v2, v6
	v_lshlrev_b64 v[4:5], 11, v[4:5]
	v_ashrrev_i32_e32 v7, 31, v6
	v_lshl_add_u64 v[4:5], s[8:9], 0, v[4:5]
	v_lshl_add_u64 v[4:5], v[6:7], 1, v[4:5]
	global_load_dwordx4 v[88:91], v[4:5], off
	v_and_b32_e32 v8, 0xfffff80, v8
	v_sub_u32_e32 v8, v3, v8
	v_bitop3_b32 v8, v9, v8, 15 bitop3:0x6c
	v_add_u32_e32 v10, 0x200, v3
	v_lshlrev_b32_e32 v14, 11, v9
	v_lshlrev_b32_e32 v8, 4, v8
	v_mov_b32_e32 v3, v10
	v_add_u32_e32 v2, 0x1000, v2
	v_add3_u32 v134, 16, v14, v8
	v_ashrrev_i32_e32 v4, 31, v3
	v_lshrrev_b32_e32 v4, 25, v4
	v_add_u32_e32 v8, v3, v4
	v_ashrrev_i32_e32 v9, 7, v8
	v_add_u32_e32 v4, s20, v9
	v_lshlrev_b32_e32 v6, 10, v9
	v_ashrrev_i32_e32 v5, 31, v4
	v_sub_u32_e32 v6, v2, v6
	v_lshlrev_b64 v[4:5], 11, v[4:5]
	v_ashrrev_i32_e32 v7, 31, v6
	v_lshl_add_u64 v[4:5], s[8:9], 0, v[4:5]
	v_lshl_add_u64 v[4:5], v[6:7], 1, v[4:5]
	global_load_dwordx4 v[92:95], v[4:5], off
	v_and_b32_e32 v8, 0xfffff80, v8
	v_sub_u32_e32 v8, v3, v8
	v_bitop3_b32 v8, v9, v8, 15 bitop3:0x6c
	v_add_u32_e32 v10, 0x200, v3
	v_lshlrev_b32_e32 v14, 11, v9
	v_lshlrev_b32_e32 v8, 4, v8
	v_mov_b32_e32 v3, v10
	v_add_u32_e32 v2, 0x1000, v2
	v_add3_u32 v135, 16, v14, v8
	v_ashrrev_i32_e32 v4, 31, v3
	v_lshrrev_b32_e32 v4, 25, v4
	v_add_u32_e32 v8, v3, v4
; #define LAS __attribute__((address_space(3)))
; template <int MODE>
; __device__ __forceinline__ void ctx_small_gemm(PREF P, unsigned char* shm) {
;     ...
;             for (int ch = tid; ch < ROWS * CPR; ch += 512) { const int row = ch / CPR, c = ch % CPR; const u32x4 v = *(const u32x4*)(Asrc + (size_t)(row_base + row) * K + c * 8);
;                 *(LAS u32x4*)(lds + row * (K * 2) + ((c ^ (row & 15)) << 4)) = v; }
	v_ashrrev_i32_e32 v9, 7, v8
	v_add_u32_e32 v4, s20, v9
	v_lshlrev_b32_e32 v6, 10, v9
	v_ashrrev_i32_e32 v5, 31, v4
	v_sub_u32_e32 v6, v2, v6
	v_lshlrev_b64 v[4:5], 11, v[4:5]
	v_ashrrev_i32_e32 v7, 31, v6
	v_lshl_add_u64 v[4:5], s[8:9], 0, v[4:5]
	v_lshl_add_u64 v[4:5], v[6:7], 1, v[4:5]
	global_load_dwordx4 v[96:99], v[4:5], off
	v_and_b32_e32 v8, 0xfffff80, v8
	v_sub_u32_e32 v8, v3, v8
	v_bitop3_b32 v8, v9, v8, 15 bitop3:0x6c
	v_add_u32_e32 v10, 0x200, v3
	v_lshlrev_b32_e32 v14, 11, v9
	v_lshlrev_b32_e32 v8, 4, v8
	v_mov_b32_e32 v3, v10
	v_add_u32_e32 v2, 0x1000, v2
	v_add3_u32 v136, 16, v14, v8
	v_ashrrev_i32_e32 v4, 31, v3
	v_lshrrev_b32_e32 v4, 25, v4
	v_add_u32_e32 v8, v3, v4
	v_ashrrev_i32_e32 v9, 7, v8
	v_add_u32_e32 v4, s20, v9
	v_lshlrev_b32_e32 v6, 10, v9
	v_ashrrev_i32_e32 v5, 31, v4
	v_sub_u32_e32 v6, v2, v6
	v_lshlrev_b64 v[4:5], 11, v[4:5]
	v_ashrrev_i32_e32 v7, 31, v6
	v_lshl_add_u64 v[4:5], s[8:9], 0, v[4:5]
	v_lshl_add_u64 v[4:5], v[6:7], 1, v[4:5]
	global_load_dwordx4 v[100:103], v[4:5], off
	v_and_b32_e32 v8, 0xfffff80, v8
	v_sub_u32_e32 v8, v3, v8
	v_bitop3_b32 v8, v9, v8, 15 bitop3:0x6c
	v_add_u32_e32 v10, 0x200, v3
	v_lshlrev_b32_e32 v14, 11, v9
	v_lshlrev_b32_e32 v8, 4, v8
	v_mov_b32_e32 v3, v10
	v_add_u32_e32 v2, 0x1000, v2
	v_add3_u32 v137, 16, v14, v8
	v_ashrrev_i32_e32 v4, 31, v3
	v_lshrrev_b32_e32 v4, 25, v4
	v_add_u32_e32 v8, v3, v4
	v_ashrrev_i32_e32 v9, 7, v8
	v_add_u32_e32 v4, s20, v9
	v_lshlrev_b32_e32 v6, 10, v9
	v_ashrrev_i32_e32 v5, 31, v4
	v_sub_u32_e32 v6, v2, v6
	v_lshlrev_b64 v[4:5], 11, v[4:5]
	v_ashrrev_i32_e32 v7, 31, v6
	v_lshl_add_u64 v[4:5], s[8:9], 0, v[4:5]
	v_lshl_add_u64 v[4:5], v[6:7], 1, v[4:5]
	global_load_dwordx4 v[104:107], v[4:5], off
	v_and_b32_e32 v8, 0xfffff80, v8
	v_sub_u32_e32 v8, v3, v8
	v_bitop3_b32 v8, v9, v8, 15 bitop3:0x6c
	v_add_u32_e32 v10, 0x200, v3
	v_lshlrev_b32_e32 v14, 11, v9
	v_lshlrev_b32_e32 v8, 4, v8
	v_mov_b32_e32 v3, v10
	v_add_u32_e32 v2, 0x1000, v2
	v_add3_u32 v138, 16, v14, v8
	v_ashrrev_i32_e32 v4, 31, v3
	v_lshrrev_b32_e32 v4, 25, v4
	v_add_u32_e32 v8, v3, v4
	v_ashrrev_i32_e32 v9, 7, v8
	v_add_u32_e32 v4, s20, v9
	v_lshlrev_b32_e32 v6, 10, v9
	v_ashrrev_i32_e32 v5, 31, v4
	v_sub_u32_e32 v6, v2, v6
	v_lshlrev_b64 v[4:5], 11, v[4:5]
	v_ashrrev_i32_e32 v7, 31, v6
	v_lshl_add_u64 v[4:5], s[8:9], 0, v[4:5]
	v_lshl_add_u64 v[4:5], v[6:7], 1, v[4:5]
	global_load_dwordx4 v[108:111], v[4:5], off
	v_and_b32_e32 v8, 0xfffff80, v8
	v_sub_u32_e32 v8, v3, v8
	v_bitop3_b32 v8, v9, v8, 15 bitop3:0x6c
	v_add_u32_e32 v10, 0x200, v3
	v_lshlrev_b32_e32 v14, 11, v9
	v_lshlrev_b32_e32 v8, 4, v8
	v_mov_b32_e32 v3, v10
	v_add_u32_e32 v2, 0x1000, v2
	v_add3_u32 v139, 16, v14, v8
	v_ashrrev_i32_e32 v4, 31, v3
	v_lshrrev_b32_e32 v4, 25, v4
	v_add_u32_e32 v8, v3, v4
	v_ashrrev_i32_e32 v9, 7, v8
	v_add_u32_e32 v4, s20, v9
	v_lshlrev_b32_e32 v6, 10, v9
	v_ashrrev_i32_e32 v5, 31, v4
	v_sub_u32_e32 v6, v2, v6
	v_lshlrev_b64 v[4:5], 11, v[4:5]
	v_ashrrev_i32_e32 v7, 31, v6
	v_lshl_add_u64 v[4:5], s[8:9], 0, v[4:5]
	v_lshl_add_u64 v[4:5], v[6:7], 1, v[4:5]
	global_load_dwordx4 v[112:115], v[4:5], off
	v_and_b32_e32 v8, 0xfffff80, v8
	v_sub_u32_e32 v8, v3, v8
	v_bitop3_b32 v8, v9, v8, 15 bitop3:0x6c
	v_add_u32_e32 v10, 0x200, v3
	v_lshlrev_b32_e32 v14, 11, v9
	v_lshlrev_b32_e32 v8, 4, v8
	v_mov_b32_e32 v3, v10
	v_add_u32_e32 v2, 0x1000, v2
	v_add3_u32 v140, 16, v14, v8
	v_ashrrev_i32_e32 v4, 31, v3
	v_lshrrev_b32_e32 v4, 25, v4
	v_add_u32_e32 v8, v3, v4
	v_ashrrev_i32_e32 v9, 7, v8
	v_add_u32_e32 v4, s20, v9
	v_lshlrev_b32_e32 v6, 10, v9
	v_ashrrev_i32_e32 v5, 31, v4
	v_sub_u32_e32 v6, v2, v6
	v_lshlrev_b64 v[4:5], 11, v[4:5]
	v_ashrrev_i32_e32 v7, 31, v6
	v_lshl_add_u64 v[4:5], s[8:9], 0, v[4:5]
	v_lshl_add_u64 v[4:5], v[6:7], 1, v[4:5]
	global_load_dwordx4 v[116:119], v[4:5], off
	v_and_b32_e32 v8, 0xfffff80, v8
	v_sub_u32_e32 v8, v3, v8
	v_bitop3_b32 v8, v9, v8, 15 bitop3:0x6c
	v_add_u32_e32 v10, 0x200, v3
	v_lshlrev_b32_e32 v14, 11, v9
	v_lshlrev_b32_e32 v8, 4, v8
	v_mov_b32_e32 v3, v10
	v_add_u32_e32 v2, 0x1000, v2
	v_add3_u32 v141, 16, v14, v8
	v_ashrrev_i32_e32 v4, 31, v3
	v_lshrrev_b32_e32 v4, 25, v4
	v_add_u32_e32 v8, v3, v4
	v_ashrrev_i32_e32 v9, 7, v8
	v_add_u32_e32 v4, s20, v9
	v_lshlrev_b32_e32 v6, 10, v9
	v_ashrrev_i32_e32 v5, 31, v4
	v_sub_u32_e32 v6, v2, v6
	v_lshlrev_b64 v[4:5], 11, v[4:5]
	v_ashrrev_i32_e32 v7, 31, v6
	v_lshl_add_u64 v[4:5], s[8:9], 0, v[4:5]
	v_lshl_add_u64 v[4:5], v[6:7], 1, v[4:5]
	global_load_dwordx4 v[120:123], v[4:5], off
	v_and_b32_e32 v8, 0xfffff80, v8
	v_sub_u32_e32 v8, v3, v8
	v_bitop3_b32 v8, v9, v8, 15 bitop3:0x6c
	v_add_u32_e32 v10, 0x200, v3
	v_lshlrev_b32_e32 v14, 11, v9
	v_lshlrev_b32_e32 v8, 4, v8
	v_mov_b32_e32 v3, v10
	v_add_u32_e32 v2, 0x1000, v2
	v_add3_u32 v142, 16, v14, v8
	v_ashrrev_i32_e32 v4, 31, v3
	v_lshrrev_b32_e32 v4, 25, v4
	v_add_u32_e32 v8, v3, v4
	v_ashrrev_i32_e32 v9, 7, v8
	v_add_u32_e32 v4, s20, v9
	v_lshlrev_b32_e32 v6, 10, v9
	v_ashrrev_i32_e32 v5, 31, v4
	v_sub_u32_e32 v6, v2, v6
	v_lshlrev_b64 v[4:5], 11, v[4:5]
	v_ashrrev_i32_e32 v7, 31, v6
	v_lshl_add_u64 v[4:5], s[8:9], 0, v[4:5]
	v_lshl_add_u64 v[4:5], v[6:7], 1, v[4:5]
	global_load_dwordx4 v[124:127], v[4:5], off
	v_and_b32_e32 v8, 0xfffff80, v8
	v_sub_u32_e32 v8, v3, v8
	v_bitop3_b32 v8, v9, v8, 15 bitop3:0x6c
	v_add_u32_e32 v10, 0x200, v3
	v_lshlrev_b32_e32 v14, 11, v9
	v_lshlrev_b32_e32 v8, 4, v8
	v_mov_b32_e32 v3, v10
	v_add_u32_e32 v2, 0x1000, v2
	v_add3_u32 v143, 16, v14, v8
	s_waitcnt vmcnt(15)
	ds_write_b128 v128, v[64:67]
	s_waitcnt vmcnt(14)
	ds_write_b128 v129, v[68:71]
	s_waitcnt vmcnt(13)
	ds_write_b128 v130, v[72:75]
	s_waitcnt vmcnt(12)
	ds_write_b128 v131, v[76:79]
	s_waitcnt vmcnt(11)
	ds_write_b128 v132, v[80:83]
	s_waitcnt vmcnt(10)
	ds_write_b128 v133, v[84:87]
	s_waitcnt vmcnt(9)
	ds_write_b128 v134, v[88:91]
	s_waitcnt vmcnt(8)
	ds_write_b128 v135, v[92:95]
	s_waitcnt vmcnt(7)
	ds_write_b128 v136, v[96:99]
	s_waitcnt vmcnt(6)
	ds_write_b128 v137, v[100:103]
	s_waitcnt vmcnt(5)
	ds_write_b128 v138, v[104:107]
	s_waitcnt vmcnt(4)
	ds_write_b128 v139, v[108:111]
	s_waitcnt vmcnt(3)
	ds_write_b128 v140, v[112:115]
	s_waitcnt vmcnt(2)
	ds_write_b128 v141, v[116:119]
	s_waitcnt vmcnt(1)
	ds_write_b128 v142, v[120:123]
	s_waitcnt vmcnt(0)
	ds_write_b128 v143, v[124:127]

; #define LAS __attribute__((address_space(3)))
; template <int MODE>
; __device__ __forceinline__ void ctx_small_gemm(PREF P, unsigned char* shm) {
;     ...
;             for (int ch = tid; ch < ROWS * CPR; ch += 512) { const int row = ch / CPR, c = ch % CPR; const u32x4 v = *(const u32x4*)(Asrc + (size_t)(row_base + row) * K + c * 8);
;                 *(LAS u32x4*)(lds + row * (K * 2) + ((c ^ (row & 15)) << 4)) = v; }
.LBB0_724:
	v_ashrrev_i32_e32 v4, 31, v3
	v_add_u32_sdwa v4, v3, v4 dst_sel:DWORD dst_unused:UNUSED_PAD src0_sel:DWORD src1_sel:BYTE_3
	v_ashrrev_i32_e32 v6, 8, v4
	v_mul_i32_i24_e32 v22, 0x100, v6
	v_add_u32_e32 v4, s10, v6
	v_ashrrev_i32_e32 v5, 31, v4
	v_lshlrev_b32_e32 v10, 3, v22
	v_lshlrev_b64 v[4:5], 12, v[4:5]
	v_sub_u32_e32 v10, v2, v10
	v_lshl_add_u64 v[4:5], s[8:9], 0, v[4:5]
	v_ashrrev_i32_e32 v11, 31, v10
	v_lshl_add_u64 v[4:5], v[10:11], 1, v[4:5]
	global_load_dwordx4 v[64:67], v[4:5], off
	v_add_u32_e32 v4, 0x200, v3
	v_sub_u32_e32 v10, v3, v22
	v_mov_b32_e32 v3, v4
	v_bitop3_b32 v4, v6, v10, 15 bitop3:0x6c
	v_lshlrev_b32_e32 v5, 12, v6
	v_lshlrev_b32_e32 v4, 4, v4
	v_add_u32_e32 v2, 0x1000, v2
	v_add3_u32 v128, 16, v5, v4
	v_ashrrev_i32_e32 v4, 31, v3
	v_add_u32_sdwa v4, v3, v4 dst_sel:DWORD dst_unused:UNUSED_PAD src0_sel:DWORD src1_sel:BYTE_3
	v_ashrrev_i32_e32 v6, 8, v4
	v_mul_i32_i24_e32 v22, 0x100, v6
	v_add_u32_e32 v4, s10, v6
	v_ashrrev_i32_e32 v5, 31, v4
	v_lshlrev_b32_e32 v10, 3, v22
	v_lshlrev_b64 v[4:5], 12, v[4:5]
	v_sub_u32_e32 v10, v2, v10
	v_lshl_add_u64 v[4:5], s[8:9], 0, v[4:5]
	v_ashrrev_i32_e32 v11, 31, v10
	v_lshl_add_u64 v[4:5], v[10:11], 1, v[4:5]
	global_load_dwordx4 v[68:71], v[4:5], off
	v_add_u32_e32 v4, 0x200, v3
	v_sub_u32_e32 v10, v3, v22
	v_mov_b32_e32 v3, v4
	v_bitop3_b32 v4, v6, v10, 15 bitop3:0x6c
	v_lshlrev_b32_e32 v5, 12, v6
	v_lshlrev_b32_e32 v4, 4, v4
	v_add_u32_e32 v2, 0x1000, v2
	v_add3_u32 v129, 16, v5, v4
	v_ashrrev_i32_e32 v4, 31, v3
	v_add_u32_sdwa v4, v3, v4 dst_sel:DWORD dst_unused:UNUSED_PAD src0_sel:DWORD src1_sel:BYTE_3
	v_ashrrev_i32_e32 v6, 8, v4
	v_mul_i32_i24_e32 v22, 0x100, v6
	v_add_u32_e32 v4, s10, v6
	v_ashrrev_i32_e32 v5, 31, v4
	v_lshlrev_b32_e32 v10, 3, v22
	v_lshlrev_b64 v[4:5], 12, v[4:5]
	v_sub_u32_e32 v10, v2, v10
	v_lshl_add_u64 v[4:5], s[8:9], 0, v[4:5]
	v_ashrrev_i32_e32 v11, 31, v10
	v_lshl_add_u64 v[4:5], v[10:11], 1, v[4:5]
	global_load_dwordx4 v[72:75], v[4:5], off
	v_add_u32_e32 v4, 0x200, v3
	v_sub_u32_e32 v10, v3, v22
	v_mov_b32_e32 v3, v4
	v_bitop3_b32 v4, v6, v10, 15 bitop3:0x6c
	v_lshlrev_b32_e32 v5, 12, v6
	v_lshlrev_b32_e32 v4, 4, v4
	v_add_u32_e32 v2, 0x1000, v2
	v_add3_u32 v130, 16, v5, v4
	v_ashrrev_i32_e32 v4, 31, v3
	v_add_u32_sdwa v4, v3, v4 dst_sel:DWORD dst_unused:UNUSED_PAD src0_sel:DWORD src1_sel:BYTE_3
	v_ashrrev_i32_e32 v6, 8, v4
	v_mul_i32_i24_e32 v22, 0x100, v6
	v_add_u32_e32 v4, s10, v6
	v_ashrrev_i32_e32 v5, 31, v4
	v_lshlrev_b32_e32 v10, 3, v22
	v_lshlrev_b64 v[4:5], 12, v[4:5]
	v_sub_u32_e32 v10, v2, v10
	v_lshl_add_u64 v[4:5], s[8:9], 0, v[4:5]
	v_ashrrev_i32_e32 v11, 31, v10
	v_lshl_add_u64 v[4:5], v[10:11], 1, v[4:5]
	global_load_dwordx4 v[76:79], v[4:5], off
	v_add_u32_e32 v4, 0x200, v3
	v_sub_u32_e32 v10, v3, v22
	v_mov_b32_e32 v3, v4
	v_bitop3_b32 v4, v6, v10, 15 bitop3:0x6c
	v_lshlrev_b32_e32 v5, 12, v6
	v_lshlrev_b32_e32 v4, 4, v4
	v_add_u32_e32 v2, 0x1000, v2
	v_add3_u32 v131, 16, v5, v4
	v_ashrrev_i32_e32 v4, 31, v3
	v_add_u32_sdwa v4, v3, v4 dst_sel:DWORD dst_unused:UNUSED_PAD src0_sel:DWORD src1_sel:BYTE_3
	v_ashrrev_i32_e32 v6, 8, v4
	v_mul_i32_i24_e32 v22, 0x100, v6
	v_add_u32_e32 v4, s10, v6
	v_ashrrev_i32_e32 v5, 31, v4
	v_lshlrev_b32_e32 v10, 3, v22
	v_lshlrev_b64 v[4:5], 12, v[4:5]
	v_sub_u32_e32 v10, v2, v10
	v_lshl_add_u64 v[4:5], s[8:9], 0, v[4:5]
	v_ashrrev_i32_e32 v11, 31, v10
	v_lshl_add_u64 v[4:5], v[10:11], 1, v[4:5]
	global_load_dwordx4 v[80:83], v[4:5], off
	v_add_u32_e32 v4, 0x200, v3
	v_sub_u32_e32 v10, v3, v22
	v_mov_b32_e32 v3, v4
	v_bitop3_b32 v4, v6, v10, 15 bitop3:0x6c
	v_lshlrev_b32_e32 v5, 12, v6
	v_lshlrev_b32_e32 v4, 4, v4
	v_add_u32_e32 v2, 0x1000, v2
	v_add3_u32 v132, 16, v5, v4
	v_ashrrev_i32_e32 v4, 31, v3
	v_add_u32_sdwa v4, v3, v4 dst_sel:DWORD dst_unused:UNUSED_PAD src0_sel:DWORD src1_sel:BYTE_3
	v_ashrrev_i32_e32 v6, 8, v4
	v_mul_i32_i24_e32 v22, 0x100, v6
	v_add_u32_e32 v4, s10, v6
	v_ashrrev_i32_e32 v5, 31, v4
	v_lshlrev_b32_e32 v10, 3, v22
	v_lshlrev_b64 v[4:5], 12, v[4:5]
	v_sub_u32_e32 v10, v2, v10
	v_lshl_add_u64 v[4:5], s[8:9], 0, v[4:5]
	v_ashrrev_i32_e32 v11, 31, v10
	v_lshl_add_u64 v[4:5], v[10:11], 1, v[4:5]
	global_load_dwordx4 v[84:87], v[4:5], off
	v_add_u32_e32 v4, 0x200, v3
	v_sub_u32_e32 v10, v3, v22
	v_mov_b32_e32 v3, v4
	v_bitop3_b32 v4, v6, v10, 15 bitop3:0x6c
	v_lshlrev_b32_e32 v5, 12, v6
	v_lshlrev_b32_e32 v4, 4, v4
	v_add_u32_e32 v2, 0x1000, v2
	v_add3_u32 v133, 16, v5, v4
	v_ashrrev_i32_e32 v4, 31, v3
	v_add_u32_sdwa v4, v3, v4 dst_sel:DWORD dst_unused:UNUSED_PAD src0_sel:DWORD src1_sel:BYTE_3
	v_ashrrev_i32_e32 v6, 8, v4
	v_mul_i32_i24_e32 v22, 0x100, v6
	v_add_u32_e32 v4, s10, v6
	v_ashrrev_i32_e32 v5, 31, v4
	v_lshlrev_b32_e32 v10, 3, v22
	v_lshlrev_b64 v[4:5], 12, v[4:5]
	v_sub_u32_e32 v10, v2, v10
	v_lshl_add_u64 v[4:5], s[8:9], 0, v[4:5]
	v_ashrrev_i32_e32 v11, 31, v10
	v_lshl_add_u64 v[4:5], v[10:11], 1, v[4:5]
	global_load_dwordx4 v[88:91], v[4:5], off
	v_add_u32_e32 v4, 0x200, v3
	v_sub_u32_e32 v10, v3, v22
	v_mov_b32_e32 v3, v4
	v_bitop3_b32 v4, v6, v10, 15 bitop3:0x6c
	v_lshlrev_b32_e32 v5, 12, v6
	v_lshlrev_b32_e32 v4, 4, v4
	v_add_u32_e32 v2, 0x1000, v2
	v_add3_u32 v134, 16, v5, v4
	v_ashrrev_i32_e32 v4, 31, v3
	v_add_u32_sdwa v4, v3, v4 dst_sel:DWORD dst_unused:UNUSED_PAD src0_sel:DWORD src1_sel:BYTE_3
	v_ashrrev_i32_e32 v6, 8, v4
	v_mul_i32_i24_e32 v22, 0x100, v6
	v_add_u32_e32 v4, s10, v6
	v_ashrrev_i32_e32 v5, 31, v4
	v_lshlrev_b32_e32 v10, 3, v22
	v_lshlrev_b64 v[4:5], 12, v[4:5]
	v_sub_u32_e32 v10, v2, v10
	v_lshl_add_u64 v[4:5], s[8:9], 0, v[4:5]
	v_ashrrev_i32_e32 v11, 31, v10
	v_lshl_add_u64 v[4:5], v[10:11], 1, v[4:5]
; #define LAS __attribute__((address_space(3)))
; template <int MODE>
; __device__ __forceinline__ void ctx_small_gemm(PREF P, unsigned char* shm) {
;     ...
;             for (int ch = tid; ch < ROWS * CPR; ch += 512) { const int row = ch / CPR, c = ch % CPR; const u32x4 v = *(const u32x4*)(Asrc + (size_t)(row_base + row) * K + c * 8);
;                 *(LAS u32x4*)(lds + row * (K * 2) + ((c ^ (row & 15)) << 4)) = v; }
	global_load_dwordx4 v[92:95], v[4:5], off
	v_add_u32_e32 v4, 0x200, v3
	v_sub_u32_e32 v10, v3, v22
	v_mov_b32_e32 v3, v4
	v_bitop3_b32 v4, v6, v10, 15 bitop3:0x6c
	v_lshlrev_b32_e32 v5, 12, v6
	v_lshlrev_b32_e32 v4, 4, v4
	v_add_u32_e32 v2, 0x1000, v2
	v_add3_u32 v135, 16, v5, v4
	v_ashrrev_i32_e32 v4, 31, v3
	v_add_u32_sdwa v4, v3, v4 dst_sel:DWORD dst_unused:UNUSED_PAD src0_sel:DWORD src1_sel:BYTE_3
	v_ashrrev_i32_e32 v6, 8, v4
	v_mul_i32_i24_e32 v22, 0x100, v6
	v_add_u32_e32 v4, s10, v6
	v_ashrrev_i32_e32 v5, 31, v4
	v_lshlrev_b32_e32 v10, 3, v22
	v_lshlrev_b64 v[4:5], 12, v[4:5]
	v_sub_u32_e32 v10, v2, v10
	v_lshl_add_u64 v[4:5], s[8:9], 0, v[4:5]
	v_ashrrev_i32_e32 v11, 31, v10
	v_lshl_add_u64 v[4:5], v[10:11], 1, v[4:5]
	global_load_dwordx4 v[96:99], v[4:5], off
	v_add_u32_e32 v4, 0x200, v3
	v_sub_u32_e32 v10, v3, v22
	v_mov_b32_e32 v3, v4
	v_bitop3_b32 v4, v6, v10, 15 bitop3:0x6c
	v_lshlrev_b32_e32 v5, 12, v6
	v_lshlrev_b32_e32 v4, 4, v4
	v_add_u32_e32 v2, 0x1000, v2
	v_add3_u32 v136, 16, v5, v4
	v_ashrrev_i32_e32 v4, 31, v3
	v_add_u32_sdwa v4, v3, v4 dst_sel:DWORD dst_unused:UNUSED_PAD src0_sel:DWORD src1_sel:BYTE_3
	v_ashrrev_i32_e32 v6, 8, v4
	v_mul_i32_i24_e32 v22, 0x100, v6
	v_add_u32_e32 v4, s10, v6
	v_ashrrev_i32_e32 v5, 31, v4
	v_lshlrev_b32_e32 v10, 3, v22
	v_lshlrev_b64 v[4:5], 12, v[4:5]
	v_sub_u32_e32 v10, v2, v10
	v_lshl_add_u64 v[4:5], s[8:9], 0, v[4:5]
	v_ashrrev_i32_e32 v11, 31, v10
	v_lshl_add_u64 v[4:5], v[10:11], 1, v[4:5]
	global_load_dwordx4 v[100:103], v[4:5], off
	v_add_u32_e32 v4, 0x200, v3
	v_sub_u32_e32 v10, v3, v22
	v_mov_b32_e32 v3, v4
	v_bitop3_b32 v4, v6, v10, 15 bitop3:0x6c
	v_lshlrev_b32_e32 v5, 12, v6
	v_lshlrev_b32_e32 v4, 4, v4
	v_add_u32_e32 v2, 0x1000, v2
	v_add3_u32 v137, 16, v5, v4
	v_ashrrev_i32_e32 v4, 31, v3
	v_add_u32_sdwa v4, v3, v4 dst_sel:DWORD dst_unused:UNUSED_PAD src0_sel:DWORD src1_sel:BYTE_3
	v_ashrrev_i32_e32 v6, 8, v4
	v_mul_i32_i24_e32 v22, 0x100, v6
	v_add_u32_e32 v4, s10, v6
	v_ashrrev_i32_e32 v5, 31, v4
	v_lshlrev_b32_e32 v10, 3, v22
	v_lshlrev_b64 v[4:5], 12, v[4:5]
	v_sub_u32_e32 v10, v2, v10
	v_lshl_add_u64 v[4:5], s[8:9], 0, v[4:5]
	v_ashrrev_i32_e32 v11, 31, v10
	v_lshl_add_u64 v[4:5], v[10:11], 1, v[4:5]
	global_load_dwordx4 v[104:107], v[4:5], off
	v_add_u32_e32 v4, 0x200, v3
	v_sub_u32_e32 v10, v3, v22
	v_mov_b32_e32 v3, v4
	v_bitop3_b32 v4, v6, v10, 15 bitop3:0x6c
	v_lshlrev_b32_e32 v5, 12, v6
	v_lshlrev_b32_e32 v4, 4, v4
	v_add_u32_e32 v2, 0x1000, v2
	v_add3_u32 v138, 16, v5, v4
	v_ashrrev_i32_e32 v4, 31, v3
	v_add_u32_sdwa v4, v3, v4 dst_sel:DWORD dst_unused:UNUSED_PAD src0_sel:DWORD src1_sel:BYTE_3
	v_ashrrev_i32_e32 v6, 8, v4
	v_mul_i32_i24_e32 v22, 0x100, v6
	v_add_u32_e32 v4, s10, v6
	v_ashrrev_i32_e32 v5, 31, v4
	v_lshlrev_b32_e32 v10, 3, v22
	v_lshlrev_b64 v[4:5], 12, v[4:5]
	v_sub_u32_e32 v10, v2, v10
	v_lshl_add_u64 v[4:5], s[8:9], 0, v[4:5]
	v_ashrrev_i32_e32 v11, 31, v10
	v_lshl_add_u64 v[4:5], v[10:11], 1, v[4:5]
	global_load_dwordx4 v[108:111], v[4:5], off
	v_add_u32_e32 v4, 0x200, v3
	v_sub_u32_e32 v10, v3, v22
	v_mov_b32_e32 v3, v4
	v_bitop3_b32 v4, v6, v10, 15 bitop3:0x6c
	v_lshlrev_b32_e32 v5, 12, v6
	v_lshlrev_b32_e32 v4, 4, v4
	v_add_u32_e32 v2, 0x1000, v2
	v_add3_u32 v139, 16, v5, v4
	v_ashrrev_i32_e32 v4, 31, v3
	v_add_u32_sdwa v4, v3, v4 dst_sel:DWORD dst_unused:UNUSED_PAD src0_sel:DWORD src1_sel:BYTE_3
	v_ashrrev_i32_e32 v6, 8, v4
	v_mul_i32_i24_e32 v22, 0x100, v6
	v_add_u32_e32 v4, s10, v6
	v_ashrrev_i32_e32 v5, 31, v4
	v_lshlrev_b32_e32 v10, 3, v22
	v_lshlrev_b64 v[4:5], 12, v[4:5]
	v_sub_u32_e32 v10, v2, v10
	v_lshl_add_u64 v[4:5], s[8:9], 0, v[4:5]
	v_ashrrev_i32_e32 v11, 31, v10
	v_lshl_add_u64 v[4:5], v[10:11], 1, v[4:5]
	global_load_dwordx4 v[112:115], v[4:5], off
	v_add_u32_e32 v4, 0x200, v3
	v_sub_u32_e32 v10, v3, v22
	v_mov_b32_e32 v3, v4
	v_bitop3_b32 v4, v6, v10, 15 bitop3:0x6c
	v_lshlrev_b32_e32 v5, 12, v6
	v_lshlrev_b32_e32 v4, 4, v4
	v_add_u32_e32 v2, 0x1000, v2
	v_add3_u32 v140, 16, v5, v4
	v_ashrrev_i32_e32 v4, 31, v3
	v_add_u32_sdwa v4, v3, v4 dst_sel:DWORD dst_unused:UNUSED_PAD src0_sel:DWORD src1_sel:BYTE_3
	v_ashrrev_i32_e32 v6, 8, v4
	v_mul_i32_i24_e32 v22, 0x100, v6
	v_add_u32_e32 v4, s10, v6
	v_ashrrev_i32_e32 v5, 31, v4
	v_lshlrev_b32_e32 v10, 3, v22
	v_lshlrev_b64 v[4:5], 12, v[4:5]
	v_sub_u32_e32 v10, v2, v10
	v_lshl_add_u64 v[4:5], s[8:9], 0, v[4:5]
	v_ashrrev_i32_e32 v11, 31, v10
	v_lshl_add_u64 v[4:5], v[10:11], 1, v[4:5]
	global_load_dwordx4 v[116:119], v[4:5], off
	v_add_u32_e32 v4, 0x200, v3
	v_sub_u32_e32 v10, v3, v22
	v_mov_b32_e32 v3, v4
	v_bitop3_b32 v4, v6, v10, 15 bitop3:0x6c
	v_lshlrev_b32_e32 v5, 12, v6
	v_lshlrev_b32_e32 v4, 4, v4
	v_add_u32_e32 v2, 0x1000, v2
	v_add3_u32 v141, 16, v5, v4
	v_ashrrev_i32_e32 v4, 31, v3
	v_add_u32_sdwa v4, v3, v4 dst_sel:DWORD dst_unused:UNUSED_PAD src0_sel:DWORD src1_sel:BYTE_3
	v_ashrrev_i32_e32 v6, 8, v4
	v_mul_i32_i24_e32 v22, 0x100, v6
	v_add_u32_e32 v4, s10, v6
	v_ashrrev_i32_e32 v5, 31, v4
	v_lshlrev_b32_e32 v10, 3, v22
	v_lshlrev_b64 v[4:5], 12, v[4:5]
	v_sub_u32_e32 v10, v2, v10
	v_lshl_add_u64 v[4:5], s[8:9], 0, v[4:5]
	v_ashrrev_i32_e32 v11, 31, v10
	v_lshl_add_u64 v[4:5], v[10:11], 1, v[4:5]
	global_load_dwordx4 v[120:123], v[4:5], off
	v_add_u32_e32 v4, 0x200, v3
	v_sub_u32_e32 v10, v3, v22
	v_mov_b32_e32 v3, v4
	v_bitop3_b32 v4, v6, v10, 15 bitop3:0x6c
	v_lshlrev_b32_e32 v5, 12, v6
	v_lshlrev_b32_e32 v4, 4, v4
	v_add_u32_e32 v2, 0x1000, v2
	v_add3_u32 v142, 16, v5, v4
	v_ashrrev_i32_e32 v4, 31, v3
	v_add_u32_sdwa v4, v3, v4 dst_sel:DWORD dst_unused:UNUSED_PAD src0_sel:DWORD src1_sel:BYTE_3
	v_ashrrev_i32_e32 v6, 8, v4
	v_mul_i32_i24_e32 v22, 0x100, v6
	v_add_u32_e32 v4, s10, v6
	v_ashrrev_i32_e32 v5, 31, v4
	v_lshlrev_b32_e32 v10, 3, v22
	v_lshlrev_b64 v[4:5], 12, v[4:5]
	v_sub_u32_e32 v10, v2, v10
	v_lshl_add_u64 v[4:5], s[8:9], 0, v[4:5]
	v_ashrrev_i32_e32 v11, 31, v10
	v_lshl_add_u64 v[4:5], v[10:11], 1, v[4:5]
	global_load_dwordx4 v[124:127], v[4:5], off
	v_add_u32_e32 v4, 0x200, v3
	v_sub_u32_e32 v10, v3, v22
	v_mov_b32_e32 v3, v4
	v_bitop3_b32 v4, v6, v10, 15 bitop3:0x6c
	v_lshlrev_b32_e32 v5, 12, v6
	v_lshlrev_b32_e32 v4, 4, v4
	v_add_u32_e32 v2, 0x1000, v2
	v_add3_u32 v143, 16, v5, v4
	s_waitcnt vmcnt(15)
	ds_write_b128 v128, v[64:67]
	s_waitcnt vmcnt(14)
	ds_write_b128 v129, v[68:71]
	s_waitcnt vmcnt(13)
	ds_write_b128 v130, v[72:75]
	s_waitcnt vmcnt(12)
	ds_write_b128 v131, v[76:79]
	s_waitcnt vmcnt(11)
	ds_write_b128 v132, v[80:83]
	s_waitcnt vmcnt(10)
	ds_write_b128 v133, v[84:87]
	s_waitcnt vmcnt(9)
	ds_write_b128 v134, v[88:91]
	s_waitcnt vmcnt(8)
	ds_write_b128 v135, v[92:95]
	s_waitcnt vmcnt(7)
	ds_write_b128 v136, v[96:99]
	s_waitcnt vmcnt(6)
	ds_write_b128 v137, v[100:103]
	s_waitcnt vmcnt(5)
	ds_write_b128 v138, v[104:107]
	s_waitcnt vmcnt(4)
	ds_write_b128 v139, v[108:111]
	s_waitcnt vmcnt(3)
	ds_write_b128 v140, v[112:115]
	s_waitcnt vmcnt(2)
	ds_write_b128 v141, v[116:119]
	s_waitcnt vmcnt(1)
	ds_write_b128 v142, v[120:123]
	s_waitcnt vmcnt(0)
	ds_write_b128 v143, v[124:127]

; #define LAS __attribute__((address_space(3)))
; template <int MODE>
; __device__ __forceinline__ void ctx_small_gemm(PREF P, unsigned char* shm) {
;     ...
;             for (int ch = tid; ch < ROWS * CPR; ch += 512) { const int row = ch / CPR, c = ch % CPR; const u32x4 v = *(const u32x4*)(Asrc + (size_t)(row_base + row) * K + c * 8);
;                 *(LAS u32x4*)(lds + row * (K * 2) + ((c ^ (row & 15)) << 4)) = v; }
.LBB0_826:
	v_ashrrev_i32_e32 v4, 31, v3
	v_lshrrev_b32_e32 v4, 25, v4
	v_add_u32_e32 v8, v3, v4
	v_ashrrev_i32_e32 v9, 7, v8
	v_add_u32_e32 v4, s31, v9
	v_lshlrev_b32_e32 v6, 10, v9
	v_ashrrev_i32_e32 v5, 31, v4
	v_sub_u32_e32 v6, v2, v6
	v_lshlrev_b64 v[4:5], 11, v[4:5]
	v_ashrrev_i32_e32 v7, 31, v6
	v_lshl_add_u64 v[4:5], s[24:25], 0, v[4:5]
	v_lshl_add_u64 v[4:5], v[6:7], 1, v[4:5]
	global_load_dwordx4 v[134:137], v[4:5], off
	v_and_b32_e32 v8, 0xfffff80, v8
	v_sub_u32_e32 v8, v3, v8
	v_bitop3_b32 v8, v9, v8, 15 bitop3:0x6c
	v_add_u32_e32 v10, 0x200, v3
	v_lshlrev_b32_e32 v60, 11, v9
	v_lshlrev_b32_e32 v8, 4, v8
	v_mov_b32_e32 v3, v10
	v_add_u32_e32 v2, 0x1000, v2
	v_add3_u32 v214, 16, v60, v8
	v_ashrrev_i32_e32 v4, 31, v3
	v_lshrrev_b32_e32 v4, 25, v4
	v_add_u32_e32 v8, v3, v4
	v_ashrrev_i32_e32 v9, 7, v8
	v_add_u32_e32 v4, s31, v9
	v_lshlrev_b32_e32 v6, 10, v9
	v_ashrrev_i32_e32 v5, 31, v4
	v_sub_u32_e32 v6, v2, v6
	v_lshlrev_b64 v[4:5], 11, v[4:5]
	v_ashrrev_i32_e32 v7, 31, v6
	v_lshl_add_u64 v[4:5], s[24:25], 0, v[4:5]
	v_lshl_add_u64 v[4:5], v[6:7], 1, v[4:5]
	global_load_dwordx4 v[138:141], v[4:5], off
	v_and_b32_e32 v8, 0xfffff80, v8
	v_sub_u32_e32 v8, v3, v8
	v_bitop3_b32 v8, v9, v8, 15 bitop3:0x6c
	v_add_u32_e32 v10, 0x200, v3
	v_lshlrev_b32_e32 v60, 11, v9
	v_lshlrev_b32_e32 v8, 4, v8
	v_mov_b32_e32 v3, v10
	v_add_u32_e32 v2, 0x1000, v2
	v_add3_u32 v215, 16, v60, v8
	v_ashrrev_i32_e32 v4, 31, v3
	v_lshrrev_b32_e32 v4, 25, v4
	v_add_u32_e32 v8, v3, v4
	v_ashrrev_i32_e32 v9, 7, v8
	v_add_u32_e32 v4, s31, v9
	v_lshlrev_b32_e32 v6, 10, v9
	v_ashrrev_i32_e32 v5, 31, v4
	v_sub_u32_e32 v6, v2, v6
	v_lshlrev_b64 v[4:5], 11, v[4:5]
	v_ashrrev_i32_e32 v7, 31, v6
	v_lshl_add_u64 v[4:5], s[24:25], 0, v[4:5]
	v_lshl_add_u64 v[4:5], v[6:7], 1, v[4:5]
	global_load_dwordx4 v[142:145], v[4:5], off
	v_and_b32_e32 v8, 0xfffff80, v8
	v_sub_u32_e32 v8, v3, v8
	v_bitop3_b32 v8, v9, v8, 15 bitop3:0x6c
	v_add_u32_e32 v10, 0x200, v3
	v_lshlrev_b32_e32 v60, 11, v9
	v_lshlrev_b32_e32 v8, 4, v8
	v_mov_b32_e32 v3, v10
	v_add_u32_e32 v2, 0x1000, v2
	v_add3_u32 v216, 16, v60, v8
	v_ashrrev_i32_e32 v4, 31, v3
	v_lshrrev_b32_e32 v4, 25, v4
	v_add_u32_e32 v8, v3, v4
	v_ashrrev_i32_e32 v9, 7, v8
	v_add_u32_e32 v4, s31, v9
	v_lshlrev_b32_e32 v6, 10, v9
	v_ashrrev_i32_e32 v5, 31, v4
	v_sub_u32_e32 v6, v2, v6
	v_lshlrev_b64 v[4:5], 11, v[4:5]
	v_ashrrev_i32_e32 v7, 31, v6
	v_lshl_add_u64 v[4:5], s[24:25], 0, v[4:5]
	v_lshl_add_u64 v[4:5], v[6:7], 1, v[4:5]
	global_load_dwordx4 v[146:149], v[4:5], off
	v_and_b32_e32 v8, 0xfffff80, v8
	v_sub_u32_e32 v8, v3, v8
	v_bitop3_b32 v8, v9, v8, 15 bitop3:0x6c
	v_add_u32_e32 v10, 0x200, v3
	v_lshlrev_b32_e32 v60, 11, v9
	v_lshlrev_b32_e32 v8, 4, v8
	v_mov_b32_e32 v3, v10
	v_add_u32_e32 v2, 0x1000, v2
	v_add3_u32 v217, 16, v60, v8
	v_ashrrev_i32_e32 v4, 31, v3
	v_lshrrev_b32_e32 v4, 25, v4
	v_add_u32_e32 v8, v3, v4
	v_ashrrev_i32_e32 v9, 7, v8
	v_add_u32_e32 v4, s31, v9
	v_lshlrev_b32_e32 v6, 10, v9
	v_ashrrev_i32_e32 v5, 31, v4
	v_sub_u32_e32 v6, v2, v6
	v_lshlrev_b64 v[4:5], 11, v[4:5]
	v_ashrrev_i32_e32 v7, 31, v6
	v_lshl_add_u64 v[4:5], s[24:25], 0, v[4:5]
	v_lshl_add_u64 v[4:5], v[6:7], 1, v[4:5]
	global_load_dwordx4 v[150:153], v[4:5], off
	v_and_b32_e32 v8, 0xfffff80, v8
	v_sub_u32_e32 v8, v3, v8
	v_bitop3_b32 v8, v9, v8, 15 bitop3:0x6c
	v_add_u32_e32 v10, 0x200, v3
	v_lshlrev_b32_e32 v60, 11, v9
	v_lshlrev_b32_e32 v8, 4, v8
	v_mov_b32_e32 v3, v10
	v_add_u32_e32 v2, 0x1000, v2
	v_add3_u32 v218, 16, v60, v8
	v_ashrrev_i32_e32 v4, 31, v3
	v_lshrrev_b32_e32 v4, 25, v4
	v_add_u32_e32 v8, v3, v4
	v_ashrrev_i32_e32 v9, 7, v8
	v_add_u32_e32 v4, s31, v9
	v_lshlrev_b32_e32 v6, 10, v9
	v_ashrrev_i32_e32 v5, 31, v4
	v_sub_u32_e32 v6, v2, v6
	v_lshlrev_b64 v[4:5], 11, v[4:5]
	v_ashrrev_i32_e32 v7, 31, v6
	v_lshl_add_u64 v[4:5], s[24:25], 0, v[4:5]
	v_lshl_add_u64 v[4:5], v[6:7], 1, v[4:5]
	global_load_dwordx4 v[154:157], v[4:5], off
	v_and_b32_e32 v8, 0xfffff80, v8
	v_sub_u32_e32 v8, v3, v8
	v_bitop3_b32 v8, v9, v8, 15 bitop3:0x6c
	v_add_u32_e32 v10, 0x200, v3
	v_lshlrev_b32_e32 v60, 11, v9
	v_lshlrev_b32_e32 v8, 4, v8
	v_mov_b32_e32 v3, v10
	v_add_u32_e32 v2, 0x1000, v2
	v_add3_u32 v219, 16, v60, v8
	v_ashrrev_i32_e32 v4, 31, v3
	v_lshrrev_b32_e32 v4, 25, v4
	v_add_u32_e32 v8, v3, v4
	v_ashrrev_i32_e32 v9, 7, v8
	v_add_u32_e32 v4, s31, v9
	v_lshlrev_b32_e32 v6, 10, v9
	v_ashrrev_i32_e32 v5, 31, v4
	v_sub_u32_e32 v6, v2, v6
	v_lshlrev_b64 v[4:5], 11, v[4:5]
	v_ashrrev_i32_e32 v7, 31, v6
	v_lshl_add_u64 v[4:5], s[24:25], 0, v[4:5]
	v_lshl_add_u64 v[4:5], v[6:7], 1, v[4:5]
	global_load_dwordx4 v[158:161], v[4:5], off
	v_and_b32_e32 v8, 0xfffff80, v8
	v_sub_u32_e32 v8, v3, v8
	v_bitop3_b32 v8, v9, v8, 15 bitop3:0x6c
	v_add_u32_e32 v10, 0x200, v3
	v_lshlrev_b32_e32 v60, 11, v9
	v_lshlrev_b32_e32 v8, 4, v8
	v_mov_b32_e32 v3, v10
	v_add_u32_e32 v2, 0x1000, v2
	v_add3_u32 v220, 16, v60, v8
	v_ashrrev_i32_e32 v4, 31, v3
	v_lshrrev_b32_e32 v4, 25, v4
	v_add_u32_e32 v8, v3, v4
	v_ashrrev_i32_e32 v9, 7, v8
	v_add_u32_e32 v4, s31, v9
	v_lshlrev_b32_e32 v6, 10, v9
	v_ashrrev_i32_e32 v5, 31, v4
	v_sub_u32_e32 v6, v2, v6
	v_lshlrev_b64 v[4:5], 11, v[4:5]
	v_ashrrev_i32_e32 v7, 31, v6
	v_lshl_add_u64 v[4:5], s[24:25], 0, v[4:5]
	v_lshl_add_u64 v[4:5], v[6:7], 1, v[4:5]
	global_load_dwordx4 v[162:165], v[4:5], off
	v_and_b32_e32 v8, 0xfffff80, v8
	v_sub_u32_e32 v8, v3, v8
	v_bitop3_b32 v8, v9, v8, 15 bitop3:0x6c
	v_add_u32_e32 v10, 0x200, v3
	v_lshlrev_b32_e32 v60, 11, v9
	v_lshlrev_b32_e32 v8, 4, v8
	v_mov_b32_e32 v3, v10
	v_add_u32_e32 v2, 0x1000, v2
	v_add3_u32 v221, 16, v60, v8
	v_ashrrev_i32_e32 v4, 31, v3
	v_lshrrev_b32_e32 v4, 25, v4
; #define LAS __attribute__((address_space(3)))
; template <int MODE>
; __device__ __forceinline__ void ctx_small_gemm(PREF P, unsigned char* shm) {
;     ...
;             for (int ch = tid; ch < ROWS * CPR; ch += 512) { const int row = ch / CPR, c = ch % CPR; const u32x4 v = *(const u32x4*)(Asrc + (size_t)(row_base + row) * K + c * 8);
;                 *(LAS u32x4*)(lds + row * (K * 2) + ((c ^ (row & 15)) << 4)) = v; }
	v_add_u32_e32 v8, v3, v4
	v_ashrrev_i32_e32 v9, 7, v8
	v_add_u32_e32 v4, s31, v9
	v_lshlrev_b32_e32 v6, 10, v9
	v_ashrrev_i32_e32 v5, 31, v4
	v_sub_u32_e32 v6, v2, v6
	v_lshlrev_b64 v[4:5], 11, v[4:5]
	v_ashrrev_i32_e32 v7, 31, v6
	v_lshl_add_u64 v[4:5], s[24:25], 0, v[4:5]
	v_lshl_add_u64 v[4:5], v[6:7], 1, v[4:5]
	global_load_dwordx4 v[168:171], v[4:5], off
	v_and_b32_e32 v8, 0xfffff80, v8
	v_sub_u32_e32 v8, v3, v8
	v_bitop3_b32 v8, v9, v8, 15 bitop3:0x6c
	v_add_u32_e32 v10, 0x200, v3
	v_lshlrev_b32_e32 v60, 11, v9
	v_lshlrev_b32_e32 v8, 4, v8
	v_mov_b32_e32 v3, v10
	v_add_u32_e32 v2, 0x1000, v2
	v_add3_u32 v222, 16, v60, v8
	v_ashrrev_i32_e32 v4, 31, v3
	v_lshrrev_b32_e32 v4, 25, v4
	v_add_u32_e32 v8, v3, v4
	v_ashrrev_i32_e32 v9, 7, v8
	v_add_u32_e32 v4, s31, v9
	v_lshlrev_b32_e32 v6, 10, v9
	v_ashrrev_i32_e32 v5, 31, v4
	v_sub_u32_e32 v6, v2, v6
	v_lshlrev_b64 v[4:5], 11, v[4:5]
	v_ashrrev_i32_e32 v7, 31, v6
	v_lshl_add_u64 v[4:5], s[24:25], 0, v[4:5]
	v_lshl_add_u64 v[4:5], v[6:7], 1, v[4:5]
	global_load_dwordx4 v[172:175], v[4:5], off
	v_and_b32_e32 v8, 0xfffff80, v8
	v_sub_u32_e32 v8, v3, v8
	v_bitop3_b32 v8, v9, v8, 15 bitop3:0x6c
	v_add_u32_e32 v10, 0x200, v3
	v_lshlrev_b32_e32 v60, 11, v9
	v_lshlrev_b32_e32 v8, 4, v8
	v_mov_b32_e32 v3, v10
	v_add_u32_e32 v2, 0x1000, v2
	v_add3_u32 v223, 16, v60, v8
	v_ashrrev_i32_e32 v4, 31, v3
	v_lshrrev_b32_e32 v4, 25, v4
	v_add_u32_e32 v8, v3, v4
	v_ashrrev_i32_e32 v9, 7, v8
	v_add_u32_e32 v4, s31, v9
	v_lshlrev_b32_e32 v6, 10, v9
	v_ashrrev_i32_e32 v5, 31, v4
	v_sub_u32_e32 v6, v2, v6
	v_lshlrev_b64 v[4:5], 11, v[4:5]
	v_ashrrev_i32_e32 v7, 31, v6
	v_lshl_add_u64 v[4:5], s[24:25], 0, v[4:5]
	v_lshl_add_u64 v[4:5], v[6:7], 1, v[4:5]
	global_load_dwordx4 v[178:181], v[4:5], off
	v_and_b32_e32 v8, 0xfffff80, v8
	v_sub_u32_e32 v8, v3, v8
	v_bitop3_b32 v8, v9, v8, 15 bitop3:0x6c
	v_add_u32_e32 v10, 0x200, v3
	v_lshlrev_b32_e32 v60, 11, v9
	v_lshlrev_b32_e32 v8, 4, v8
	v_mov_b32_e32 v3, v10
	v_add_u32_e32 v2, 0x1000, v2
	v_add3_u32 v224, 16, v60, v8
	v_ashrrev_i32_e32 v4, 31, v3
	v_lshrrev_b32_e32 v4, 25, v4
	v_add_u32_e32 v8, v3, v4
	v_ashrrev_i32_e32 v9, 7, v8
	v_add_u32_e32 v4, s31, v9
	v_lshlrev_b32_e32 v6, 10, v9
	v_ashrrev_i32_e32 v5, 31, v4
	v_sub_u32_e32 v6, v2, v6
	v_lshlrev_b64 v[4:5], 11, v[4:5]
	v_ashrrev_i32_e32 v7, 31, v6
	v_lshl_add_u64 v[4:5], s[24:25], 0, v[4:5]
	v_lshl_add_u64 v[4:5], v[6:7], 1, v[4:5]
	global_load_dwordx4 v[182:185], v[4:5], off
	v_and_b32_e32 v8, 0xfffff80, v8
	v_sub_u32_e32 v8, v3, v8
	v_bitop3_b32 v8, v9, v8, 15 bitop3:0x6c
	v_add_u32_e32 v10, 0x200, v3
	v_lshlrev_b32_e32 v60, 11, v9
	v_lshlrev_b32_e32 v8, 4, v8
	v_mov_b32_e32 v3, v10
	v_add_u32_e32 v2, 0x1000, v2
	v_add3_u32 v225, 16, v60, v8
	v_ashrrev_i32_e32 v4, 31, v3
	v_lshrrev_b32_e32 v4, 25, v4
	v_add_u32_e32 v8, v3, v4
	v_ashrrev_i32_e32 v9, 7, v8
	v_add_u32_e32 v4, s31, v9
	v_lshlrev_b32_e32 v6, 10, v9
	v_ashrrev_i32_e32 v5, 31, v4
	v_sub_u32_e32 v6, v2, v6
	v_lshlrev_b64 v[4:5], 11, v[4:5]
	v_ashrrev_i32_e32 v7, 31, v6
	v_lshl_add_u64 v[4:5], s[24:25], 0, v[4:5]
	v_lshl_add_u64 v[4:5], v[6:7], 1, v[4:5]
	global_load_dwordx4 v[186:189], v[4:5], off
	v_and_b32_e32 v8, 0xfffff80, v8
	v_sub_u32_e32 v8, v3, v8
	v_bitop3_b32 v8, v9, v8, 15 bitop3:0x6c
	v_add_u32_e32 v10, 0x200, v3
	v_lshlrev_b32_e32 v60, 11, v9
	v_lshlrev_b32_e32 v8, 4, v8
	v_mov_b32_e32 v3, v10
	v_add_u32_e32 v2, 0x1000, v2
	v_add3_u32 v226, 16, v60, v8
	v_ashrrev_i32_e32 v4, 31, v3
	v_lshrrev_b32_e32 v4, 25, v4
	v_add_u32_e32 v8, v3, v4
	v_ashrrev_i32_e32 v9, 7, v8
	v_add_u32_e32 v4, s31, v9
	v_lshlrev_b32_e32 v6, 10, v9
	v_ashrrev_i32_e32 v5, 31, v4
	v_sub_u32_e32 v6, v2, v6
	v_lshlrev_b64 v[4:5], 11, v[4:5]
	v_ashrrev_i32_e32 v7, 31, v6
	v_lshl_add_u64 v[4:5], s[24:25], 0, v[4:5]
	v_lshl_add_u64 v[4:5], v[6:7], 1, v[4:5]
	global_load_dwordx4 v[190:193], v[4:5], off
	v_and_b32_e32 v8, 0xfffff80, v8
	v_sub_u32_e32 v8, v3, v8
	v_bitop3_b32 v8, v9, v8, 15 bitop3:0x6c
	v_add_u32_e32 v10, 0x200, v3
	v_lshlrev_b32_e32 v60, 11, v9
	v_lshlrev_b32_e32 v8, 4, v8
	v_mov_b32_e32 v3, v10
	v_add_u32_e32 v2, 0x1000, v2
	v_add3_u32 v227, 16, v60, v8
	v_ashrrev_i32_e32 v4, 31, v3
	v_lshrrev_b32_e32 v4, 25, v4
	v_add_u32_e32 v8, v3, v4
	v_ashrrev_i32_e32 v9, 7, v8
	v_add_u32_e32 v4, s31, v9
	v_lshlrev_b32_e32 v6, 10, v9
	v_ashrrev_i32_e32 v5, 31, v4
	v_sub_u32_e32 v6, v2, v6
	v_lshlrev_b64 v[4:5], 11, v[4:5]
	v_ashrrev_i32_e32 v7, 31, v6
	v_lshl_add_u64 v[4:5], s[24:25], 0, v[4:5]
	v_lshl_add_u64 v[4:5], v[6:7], 1, v[4:5]
	global_load_dwordx4 v[194:197], v[4:5], off
	v_and_b32_e32 v8, 0xfffff80, v8
	v_sub_u32_e32 v8, v3, v8
	v_bitop3_b32 v8, v9, v8, 15 bitop3:0x6c
	v_add_u32_e32 v10, 0x200, v3
	v_lshlrev_b32_e32 v60, 11, v9
	v_lshlrev_b32_e32 v8, 4, v8
	v_mov_b32_e32 v3, v10
	v_add_u32_e32 v2, 0x1000, v2
	v_add3_u32 v228, 16, v60, v8
	v_ashrrev_i32_e32 v4, 31, v3
	v_lshrrev_b32_e32 v4, 25, v4
	v_add_u32_e32 v8, v3, v4
	v_ashrrev_i32_e32 v9, 7, v8
	v_add_u32_e32 v4, s31, v9
	v_lshlrev_b32_e32 v6, 10, v9
	v_ashrrev_i32_e32 v5, 31, v4
	v_sub_u32_e32 v6, v2, v6
	v_lshlrev_b64 v[4:5], 11, v[4:5]
	v_ashrrev_i32_e32 v7, 31, v6
	v_lshl_add_u64 v[4:5], s[24:25], 0, v[4:5]
	v_lshl_add_u64 v[4:5], v[6:7], 1, v[4:5]
	global_load_dwordx4 v[198:201], v[4:5], off
	v_and_b32_e32 v8, 0xfffff80, v8
	v_sub_u32_e32 v8, v3, v8
	v_bitop3_b32 v8, v9, v8, 15 bitop3:0x6c
	v_add_u32_e32 v10, 0x200, v3
	v_lshlrev_b32_e32 v60, 11, v9
	v_lshlrev_b32_e32 v8, 4, v8
	v_mov_b32_e32 v3, v10
	v_add_u32_e32 v2, 0x1000, v2
	v_add3_u32 v229, 16, v60, v8
	s_waitcnt vmcnt(15)
	ds_write_b128 v214, v[134:137]
	s_waitcnt vmcnt(14)
	ds_write_b128 v215, v[138:141]
	s_waitcnt vmcnt(13)
	ds_write_b128 v216, v[142:145]
	s_waitcnt vmcnt(12)
	ds_write_b128 v217, v[146:149]
	s_waitcnt vmcnt(11)
	ds_write_b128 v218, v[150:153]
	s_waitcnt vmcnt(10)
	ds_write_b128 v219, v[154:157]
	s_waitcnt vmcnt(9)
	ds_write_b128 v220, v[158:161]
	s_waitcnt vmcnt(8)
	ds_write_b128 v221, v[162:165]
	s_waitcnt vmcnt(7)
	ds_write_b128 v222, v[168:171]
	s_waitcnt vmcnt(6)
	ds_write_b128 v223, v[172:175]
	s_waitcnt vmcnt(5)
	ds_write_b128 v224, v[178:181]
	s_waitcnt vmcnt(4)
	ds_write_b128 v225, v[182:185]
	s_waitcnt vmcnt(3)
	ds_write_b128 v226, v[186:189]
	s_waitcnt vmcnt(2)
	ds_write_b128 v227, v[190:193]
	s_waitcnt vmcnt(1)
	ds_write_b128 v228, v[194:197]
	s_waitcnt vmcnt(0)
	ds_write_b128 v229, v[198:201]

; #define LAS __attribute__((address_space(3)))
; template <int MODE>
; __device__ __forceinline__ void ctx_small_gemm(PREF P, unsigned char* shm) {
;     ...
;             for (int ch = tid; ch < ROWS * CPR; ch += 512) { const int row = ch / CPR, c = ch % CPR; const u32x4 v = *(const u32x4*)(Asrc + (size_t)(row_base + row) * K + c * 8);
;                 *(LAS u32x4*)(lds + row * (K * 2) + ((c ^ (row & 15)) << 4)) = v; }
.LBB0_938:
	v_ashrrev_i32_e32 v4, 31, v3
	v_add_u32_sdwa v4, v3, v4 dst_sel:DWORD dst_unused:UNUSED_PAD src0_sel:DWORD src1_sel:BYTE_3
	v_ashrrev_i32_e32 v8, 8, v4
	v_mul_i32_i24_e32 v9, 0x100, v8
	v_add_u32_e32 v4, s21, v8
	v_ashrrev_i32_e32 v5, 31, v4
	v_lshlrev_b32_e32 v6, 3, v9
	v_lshlrev_b64 v[4:5], 12, v[4:5]
	v_sub_u32_e32 v6, v2, v6
	v_lshl_add_u64 v[4:5], s[8:9], 0, v[4:5]
	v_ashrrev_i32_e32 v7, 31, v6
	v_lshl_add_u64 v[4:5], v[6:7], 1, v[4:5]
	global_load_dwordx4 v[64:67], v[4:5], off
	v_sub_u32_e32 v9, v3, v9
	v_lshlrev_b32_e32 v14, 12, v8
	v_bitop3_b32 v8, v8, v9, 15 bitop3:0x6c
	v_add_u32_e32 v10, 0x200, v3
	v_lshlrev_b32_e32 v8, 4, v8
	v_mov_b32_e32 v3, v10
	v_add_u32_e32 v2, 0x1000, v2
	v_add3_u32 v128, 16, v14, v8
	v_ashrrev_i32_e32 v4, 31, v3
	v_add_u32_sdwa v4, v3, v4 dst_sel:DWORD dst_unused:UNUSED_PAD src0_sel:DWORD src1_sel:BYTE_3
	v_ashrrev_i32_e32 v8, 8, v4
	v_mul_i32_i24_e32 v9, 0x100, v8
	v_add_u32_e32 v4, s21, v8
	v_ashrrev_i32_e32 v5, 31, v4
	v_lshlrev_b32_e32 v6, 3, v9
	v_lshlrev_b64 v[4:5], 12, v[4:5]
	v_sub_u32_e32 v6, v2, v6
	v_lshl_add_u64 v[4:5], s[8:9], 0, v[4:5]
	v_ashrrev_i32_e32 v7, 31, v6
	v_lshl_add_u64 v[4:5], v[6:7], 1, v[4:5]
	global_load_dwordx4 v[68:71], v[4:5], off
	v_sub_u32_e32 v9, v3, v9
	v_lshlrev_b32_e32 v14, 12, v8
	v_bitop3_b32 v8, v8, v9, 15 bitop3:0x6c
	v_add_u32_e32 v10, 0x200, v3
	v_lshlrev_b32_e32 v8, 4, v8
	v_mov_b32_e32 v3, v10
	v_add_u32_e32 v2, 0x1000, v2
	v_add3_u32 v129, 16, v14, v8
	v_ashrrev_i32_e32 v4, 31, v3
	v_add_u32_sdwa v4, v3, v4 dst_sel:DWORD dst_unused:UNUSED_PAD src0_sel:DWORD src1_sel:BYTE_3
	v_ashrrev_i32_e32 v8, 8, v4
	v_mul_i32_i24_e32 v9, 0x100, v8
	v_add_u32_e32 v4, s21, v8
	v_ashrrev_i32_e32 v5, 31, v4
	v_lshlrev_b32_e32 v6, 3, v9
	v_lshlrev_b64 v[4:5], 12, v[4:5]
	v_sub_u32_e32 v6, v2, v6
	v_lshl_add_u64 v[4:5], s[8:9], 0, v[4:5]
	v_ashrrev_i32_e32 v7, 31, v6
	v_lshl_add_u64 v[4:5], v[6:7], 1, v[4:5]
	global_load_dwordx4 v[72:75], v[4:5], off
	v_sub_u32_e32 v9, v3, v9
	v_lshlrev_b32_e32 v14, 12, v8
	v_bitop3_b32 v8, v8, v9, 15 bitop3:0x6c
	v_add_u32_e32 v10, 0x200, v3
	v_lshlrev_b32_e32 v8, 4, v8
	v_mov_b32_e32 v3, v10
	v_add_u32_e32 v2, 0x1000, v2
	v_add3_u32 v130, 16, v14, v8
	v_ashrrev_i32_e32 v4, 31, v3
	v_add_u32_sdwa v4, v3, v4 dst_sel:DWORD dst_unused:UNUSED_PAD src0_sel:DWORD src1_sel:BYTE_3
	v_ashrrev_i32_e32 v8, 8, v4
	v_mul_i32_i24_e32 v9, 0x100, v8
	v_add_u32_e32 v4, s21, v8
	v_ashrrev_i32_e32 v5, 31, v4
	v_lshlrev_b32_e32 v6, 3, v9
	v_lshlrev_b64 v[4:5], 12, v[4:5]
	v_sub_u32_e32 v6, v2, v6
	v_lshl_add_u64 v[4:5], s[8:9], 0, v[4:5]
	v_ashrrev_i32_e32 v7, 31, v6
	v_lshl_add_u64 v[4:5], v[6:7], 1, v[4:5]
	global_load_dwordx4 v[76:79], v[4:5], off
	v_sub_u32_e32 v9, v3, v9
	v_lshlrev_b32_e32 v14, 12, v8
	v_bitop3_b32 v8, v8, v9, 15 bitop3:0x6c
	v_add_u32_e32 v10, 0x200, v3
	v_lshlrev_b32_e32 v8, 4, v8
	v_mov_b32_e32 v3, v10
	v_add_u32_e32 v2, 0x1000, v2
	v_add3_u32 v131, 16, v14, v8
	v_ashrrev_i32_e32 v4, 31, v3
	v_add_u32_sdwa v4, v3, v4 dst_sel:DWORD dst_unused:UNUSED_PAD src0_sel:DWORD src1_sel:BYTE_3
	v_ashrrev_i32_e32 v8, 8, v4
	v_mul_i32_i24_e32 v9, 0x100, v8
	v_add_u32_e32 v4, s21, v8
	v_ashrrev_i32_e32 v5, 31, v4
	v_lshlrev_b32_e32 v6, 3, v9
	v_lshlrev_b64 v[4:5], 12, v[4:5]
	v_sub_u32_e32 v6, v2, v6
	v_lshl_add_u64 v[4:5], s[8:9], 0, v[4:5]
	v_ashrrev_i32_e32 v7, 31, v6
	v_lshl_add_u64 v[4:5], v[6:7], 1, v[4:5]
	global_load_dwordx4 v[80:83], v[4:5], off
	v_sub_u32_e32 v9, v3, v9
	v_lshlrev_b32_e32 v14, 12, v8
	v_bitop3_b32 v8, v8, v9, 15 bitop3:0x6c
	v_add_u32_e32 v10, 0x200, v3
	v_lshlrev_b32_e32 v8, 4, v8
	v_mov_b32_e32 v3, v10
	v_add_u32_e32 v2, 0x1000, v2
	v_add3_u32 v132, 16, v14, v8
	v_ashrrev_i32_e32 v4, 31, v3
	v_add_u32_sdwa v4, v3, v4 dst_sel:DWORD dst_unused:UNUSED_PAD src0_sel:DWORD src1_sel:BYTE_3
	v_ashrrev_i32_e32 v8, 8, v4
	v_mul_i32_i24_e32 v9, 0x100, v8
	v_add_u32_e32 v4, s21, v8
	v_ashrrev_i32_e32 v5, 31, v4
	v_lshlrev_b32_e32 v6, 3, v9
	v_lshlrev_b64 v[4:5], 12, v[4:5]
	v_sub_u32_e32 v6, v2, v6
	v_lshl_add_u64 v[4:5], s[8:9], 0, v[4:5]
	v_ashrrev_i32_e32 v7, 31, v6
	v_lshl_add_u64 v[4:5], v[6:7], 1, v[4:5]
	global_load_dwordx4 v[84:87], v[4:5], off
	v_sub_u32_e32 v9, v3, v9
	v_lshlrev_b32_e32 v14, 12, v8
	v_bitop3_b32 v8, v8, v9, 15 bitop3:0x6c
	v_add_u32_e32 v10, 0x200, v3
	v_lshlrev_b32_e32 v8, 4, v8
	v_mov_b32_e32 v3, v10
	v_add_u32_e32 v2, 0x1000, v2
	v_add3_u32 v133, 16, v14, v8
	v_ashrrev_i32_e32 v4, 31, v3
	v_add_u32_sdwa v4, v3, v4 dst_sel:DWORD dst_unused:UNUSED_PAD src0_sel:DWORD src1_sel:BYTE_3
	v_ashrrev_i32_e32 v8, 8, v4
	v_mul_i32_i24_e32 v9, 0x100, v8
	v_add_u32_e32 v4, s21, v8
	v_ashrrev_i32_e32 v5, 31, v4
	v_lshlrev_b32_e32 v6, 3, v9
	v_lshlrev_b64 v[4:5], 12, v[4:5]
	v_sub_u32_e32 v6, v2, v6
	v_lshl_add_u64 v[4:5], s[8:9], 0, v[4:5]
	v_ashrrev_i32_e32 v7, 31, v6
	v_lshl_add_u64 v[4:5], v[6:7], 1, v[4:5]
	global_load_dwordx4 v[88:91], v[4:5], off
	v_sub_u32_e32 v9, v3, v9
	v_lshlrev_b32_e32 v14, 12, v8
	v_bitop3_b32 v8, v8, v9, 15 bitop3:0x6c
	v_add_u32_e32 v10, 0x200, v3
	v_lshlrev_b32_e32 v8, 4, v8
	v_mov_b32_e32 v3, v10
	v_add_u32_e32 v2, 0x1000, v2
	v_add3_u32 v134, 16, v14, v8
	v_ashrrev_i32_e32 v4, 31, v3
	v_add_u32_sdwa v4, v3, v4 dst_sel:DWORD dst_unused:UNUSED_PAD src0_sel:DWORD src1_sel:BYTE_3
	v_ashrrev_i32_e32 v8, 8, v4
	v_mul_i32_i24_e32 v9, 0x100, v8
	v_add_u32_e32 v4, s21, v8
	v_ashrrev_i32_e32 v5, 31, v4
	v_lshlrev_b32_e32 v6, 3, v9
	v_lshlrev_b64 v[4:5], 12, v[4:5]
	v_sub_u32_e32 v6, v2, v6
	v_lshl_add_u64 v[4:5], s[8:9], 0, v[4:5]
	v_ashrrev_i32_e32 v7, 31, v6
	v_lshl_add_u64 v[4:5], v[6:7], 1, v[4:5]
	global_load_dwordx4 v[92:95], v[4:5], off
	v_sub_u32_e32 v9, v3, v9
; #define LAS __attribute__((address_space(3)))
; template <int MODE>
; __device__ __forceinline__ void ctx_small_gemm(PREF P, unsigned char* shm) {
;     ...
;             for (int ch = tid; ch < ROWS * CPR; ch += 512) { const int row = ch / CPR, c = ch % CPR; const u32x4 v = *(const u32x4*)(Asrc + (size_t)(row_base + row) * K + c * 8);
;                 *(LAS u32x4*)(lds + row * (K * 2) + ((c ^ (row & 15)) << 4)) = v; }
	v_lshlrev_b32_e32 v14, 12, v8
	v_bitop3_b32 v8, v8, v9, 15 bitop3:0x6c
	v_add_u32_e32 v10, 0x200, v3
	v_lshlrev_b32_e32 v8, 4, v8
	v_mov_b32_e32 v3, v10
	v_add_u32_e32 v2, 0x1000, v2
	v_add3_u32 v135, 16, v14, v8
	v_ashrrev_i32_e32 v4, 31, v3
	v_add_u32_sdwa v4, v3, v4 dst_sel:DWORD dst_unused:UNUSED_PAD src0_sel:DWORD src1_sel:BYTE_3
	v_ashrrev_i32_e32 v8, 8, v4
	v_mul_i32_i24_e32 v9, 0x100, v8
	v_add_u32_e32 v4, s21, v8
	v_ashrrev_i32_e32 v5, 31, v4
	v_lshlrev_b32_e32 v6, 3, v9
	v_lshlrev_b64 v[4:5], 12, v[4:5]
	v_sub_u32_e32 v6, v2, v6
	v_lshl_add_u64 v[4:5], s[8:9], 0, v[4:5]
	v_ashrrev_i32_e32 v7, 31, v6
	v_lshl_add_u64 v[4:5], v[6:7], 1, v[4:5]
	global_load_dwordx4 v[96:99], v[4:5], off
	v_sub_u32_e32 v9, v3, v9
	v_lshlrev_b32_e32 v14, 12, v8
	v_bitop3_b32 v8, v8, v9, 15 bitop3:0x6c
	v_add_u32_e32 v10, 0x200, v3
	v_lshlrev_b32_e32 v8, 4, v8
	v_mov_b32_e32 v3, v10
	v_add_u32_e32 v2, 0x1000, v2
	v_add3_u32 v136, 16, v14, v8
	v_ashrrev_i32_e32 v4, 31, v3
	v_add_u32_sdwa v4, v3, v4 dst_sel:DWORD dst_unused:UNUSED_PAD src0_sel:DWORD src1_sel:BYTE_3
	v_ashrrev_i32_e32 v8, 8, v4
	v_mul_i32_i24_e32 v9, 0x100, v8
	v_add_u32_e32 v4, s21, v8
	v_ashrrev_i32_e32 v5, 31, v4
	v_lshlrev_b32_e32 v6, 3, v9
	v_lshlrev_b64 v[4:5], 12, v[4:5]
	v_sub_u32_e32 v6, v2, v6
	v_lshl_add_u64 v[4:5], s[8:9], 0, v[4:5]
	v_ashrrev_i32_e32 v7, 31, v6
	v_lshl_add_u64 v[4:5], v[6:7], 1, v[4:5]
	global_load_dwordx4 v[100:103], v[4:5], off
	v_sub_u32_e32 v9, v3, v9
	v_lshlrev_b32_e32 v14, 12, v8
	v_bitop3_b32 v8, v8, v9, 15 bitop3:0x6c
	v_add_u32_e32 v10, 0x200, v3
	v_lshlrev_b32_e32 v8, 4, v8
	v_mov_b32_e32 v3, v10
	v_add_u32_e32 v2, 0x1000, v2
	v_add3_u32 v137, 16, v14, v8
	v_ashrrev_i32_e32 v4, 31, v3
	v_add_u32_sdwa v4, v3, v4 dst_sel:DWORD dst_unused:UNUSED_PAD src0_sel:DWORD src1_sel:BYTE_3
	v_ashrrev_i32_e32 v8, 8, v4
	v_mul_i32_i24_e32 v9, 0x100, v8
	v_add_u32_e32 v4, s21, v8
	v_ashrrev_i32_e32 v5, 31, v4
	v_lshlrev_b32_e32 v6, 3, v9
	v_lshlrev_b64 v[4:5], 12, v[4:5]
	v_sub_u32_e32 v6, v2, v6
	v_lshl_add_u64 v[4:5], s[8:9], 0, v[4:5]
	v_ashrrev_i32_e32 v7, 31, v6
	v_lshl_add_u64 v[4:5], v[6:7], 1, v[4:5]
	global_load_dwordx4 v[104:107], v[4:5], off
	v_sub_u32_e32 v9, v3, v9
	v_lshlrev_b32_e32 v14, 12, v8
	v_bitop3_b32 v8, v8, v9, 15 bitop3:0x6c
	v_add_u32_e32 v10, 0x200, v3
	v_lshlrev_b32_e32 v8, 4, v8
	v_mov_b32_e32 v3, v10
	v_add_u32_e32 v2, 0x1000, v2
	v_add3_u32 v138, 16, v14, v8
	v_ashrrev_i32_e32 v4, 31, v3
	v_add_u32_sdwa v4, v3, v4 dst_sel:DWORD dst_unused:UNUSED_PAD src0_sel:DWORD src1_sel:BYTE_3
	v_ashrrev_i32_e32 v8, 8, v4
	v_mul_i32_i24_e32 v9, 0x100, v8
	v_add_u32_e32 v4, s21, v8
	v_ashrrev_i32_e32 v5, 31, v4
	v_lshlrev_b32_e32 v6, 3, v9
	v_lshlrev_b64 v[4:5], 12, v[4:5]
	v_sub_u32_e32 v6, v2, v6
	v_lshl_add_u64 v[4:5], s[8:9], 0, v[4:5]
	v_ashrrev_i32_e32 v7, 31, v6
	v_lshl_add_u64 v[4:5], v[6:7], 1, v[4:5]
	global_load_dwordx4 v[108:111], v[4:5], off
	v_sub_u32_e32 v9, v3, v9
	v_lshlrev_b32_e32 v14, 12, v8
	v_bitop3_b32 v8, v8, v9, 15 bitop3:0x6c
	v_add_u32_e32 v10, 0x200, v3
	v_lshlrev_b32_e32 v8, 4, v8
	v_mov_b32_e32 v3, v10
	v_add_u32_e32 v2, 0x1000, v2
	v_add3_u32 v139, 16, v14, v8
	v_ashrrev_i32_e32 v4, 31, v3
	v_add_u32_sdwa v4, v3, v4 dst_sel:DWORD dst_unused:UNUSED_PAD src0_sel:DWORD src1_sel:BYTE_3
	v_ashrrev_i32_e32 v8, 8, v4
	v_mul_i32_i24_e32 v9, 0x100, v8
	v_add_u32_e32 v4, s21, v8
	v_ashrrev_i32_e32 v5, 31, v4
	v_lshlrev_b32_e32 v6, 3, v9
	v_lshlrev_b64 v[4:5], 12, v[4:5]
	v_sub_u32_e32 v6, v2, v6
	v_lshl_add_u64 v[4:5], s[8:9], 0, v[4:5]
	v_ashrrev_i32_e32 v7, 31, v6
	v_lshl_add_u64 v[4:5], v[6:7], 1, v[4:5]
	global_load_dwordx4 v[112:115], v[4:5], off
	v_sub_u32_e32 v9, v3, v9
	v_lshlrev_b32_e32 v14, 12, v8
	v_bitop3_b32 v8, v8, v9, 15 bitop3:0x6c
	v_add_u32_e32 v10, 0x200, v3
	v_lshlrev_b32_e32 v8, 4, v8
	v_mov_b32_e32 v3, v10
	v_add_u32_e32 v2, 0x1000, v2
	v_add3_u32 v140, 16, v14, v8
	v_ashrrev_i32_e32 v4, 31, v3
	v_add_u32_sdwa v4, v3, v4 dst_sel:DWORD dst_unused:UNUSED_PAD src0_sel:DWORD src1_sel:BYTE_3
	v_ashrrev_i32_e32 v8, 8, v4
	v_mul_i32_i24_e32 v9, 0x100, v8
	v_add_u32_e32 v4, s21, v8
	v_ashrrev_i32_e32 v5, 31, v4
	v_lshlrev_b32_e32 v6, 3, v9
	v_lshlrev_b64 v[4:5], 12, v[4:5]
	v_sub_u32_e32 v6, v2, v6
	v_lshl_add_u64 v[4:5], s[8:9], 0, v[4:5]
	v_ashrrev_i32_e32 v7, 31, v6
	v_lshl_add_u64 v[4:5], v[6:7], 1, v[4:5]
	global_load_dwordx4 v[116:119], v[4:5], off
	v_sub_u32_e32 v9, v3, v9
	v_lshlrev_b32_e32 v14, 12, v8
	v_bitop3_b32 v8, v8, v9, 15 bitop3:0x6c
	v_add_u32_e32 v10, 0x200, v3
	v_lshlrev_b32_e32 v8, 4, v8
	v_mov_b32_e32 v3, v10
	v_add_u32_e32 v2, 0x1000, v2
	v_add3_u32 v141, 16, v14, v8
	v_ashrrev_i32_e32 v4, 31, v3
	v_add_u32_sdwa v4, v3, v4 dst_sel:DWORD dst_unused:UNUSED_PAD src0_sel:DWORD src1_sel:BYTE_3
	v_ashrrev_i32_e32 v8, 8, v4
	v_mul_i32_i24_e32 v9, 0x100, v8
	v_add_u32_e32 v4, s21, v8
	v_ashrrev_i32_e32 v5, 31, v4
	v_lshlrev_b32_e32 v6, 3, v9
	v_lshlrev_b64 v[4:5], 12, v[4:5]
	v_sub_u32_e32 v6, v2, v6
	v_lshl_add_u64 v[4:5], s[8:9], 0, v[4:5]
	v_ashrrev_i32_e32 v7, 31, v6
	v_lshl_add_u64 v[4:5], v[6:7], 1, v[4:5]
	global_load_dwordx4 v[120:123], v[4:5], off
	v_sub_u32_e32 v9, v3, v9
	v_lshlrev_b32_e32 v14, 12, v8
	v_bitop3_b32 v8, v8, v9, 15 bitop3:0x6c
	v_add_u32_e32 v10, 0x200, v3
	v_lshlrev_b32_e32 v8, 4, v8
	v_mov_b32_e32 v3, v10
	v_add_u32_e32 v2, 0x1000, v2
	v_add3_u32 v142, 16, v14, v8
	v_ashrrev_i32_e32 v4, 31, v3
	v_add_u32_sdwa v4, v3, v4 dst_sel:DWORD dst_unused:UNUSED_PAD src0_sel:DWORD src1_sel:BYTE_3
	v_ashrrev_i32_e32 v8, 8, v4
	v_mul_i32_i24_e32 v9, 0x100, v8
	v_add_u32_e32 v4, s21, v8
	v_ashrrev_i32_e32 v5, 31, v4
	v_lshlrev_b32_e32 v6, 3, v9
	v_lshlrev_b64 v[4:5], 12, v[4:5]
	v_sub_u32_e32 v6, v2, v6
	v_lshl_add_u64 v[4:5], s[8:9], 0, v[4:5]
	v_ashrrev_i32_e32 v7, 31, v6
	v_lshl_add_u64 v[4:5], v[6:7], 1, v[4:5]
	global_load_dwordx4 v[124:127], v[4:5], off
	v_sub_u32_e32 v9, v3, v9
	v_lshlrev_b32_e32 v14, 12, v8
	v_bitop3_b32 v8, v8, v9, 15 bitop3:0x6c
	v_add_u32_e32 v10, 0x200, v3
	v_lshlrev_b32_e32 v8, 4, v8
	v_mov_b32_e32 v3, v10
	v_add_u32_e32 v2, 0x1000, v2
	v_add3_u32 v143, 16, v14, v8
	s_waitcnt vmcnt(15)
	ds_write_b128 v128, v[64:67]
	s_waitcnt vmcnt(14)
	ds_write_b128 v129, v[68:71]
	s_waitcnt vmcnt(13)
	ds_write_b128 v130, v[72:75]
	s_waitcnt vmcnt(12)
	ds_write_b128 v131, v[76:79]
	s_waitcnt vmcnt(11)
	ds_write_b128 v132, v[80:83]
	s_waitcnt vmcnt(10)
	ds_write_b128 v133, v[84:87]
	s_waitcnt vmcnt(9)
	ds_write_b128 v134, v[88:91]
	s_waitcnt vmcnt(8)
	ds_write_b128 v135, v[92:95]
	s_waitcnt vmcnt(7)
	ds_write_b128 v136, v[96:99]
	s_waitcnt vmcnt(6)
	ds_write_b128 v137, v[100:103]
	s_waitcnt vmcnt(5)
	ds_write_b128 v138, v[104:107]
	s_waitcnt vmcnt(4)
	ds_write_b128 v139, v[108:111]
	s_waitcnt vmcnt(3)
	ds_write_b128 v140, v[112:115]
	s_waitcnt vmcnt(2)
	ds_write_b128 v141, v[116:119]
	s_waitcnt vmcnt(1)
	ds_write_b128 v142, v[120:123]
	s_waitcnt vmcnt(0)
	ds_write_b128 v143, v[124:127]
